# P0: rows loop gain/b_f loads de-serialised + next-row x prefetch; forget-weight LDS fill in one round of 16B loads
# speedup vs baseline: 1.0216x; 1.0092x over previous
.LBB0_99:
	s_or_b64 exec, exec, s[8:9]
	v_lshrrev_b32_e32 v5, 9, v208
	v_sub_u32_e32 v2, 30, v5
	v_and_b32_e32 v1, 15, v208
	v_lshrrev_b32_e32 v2, 1, v2
	v_lshlrev_b32_e32 v4, 12, v1
	v_add_u32_e32 v7, 1, v2
	v_add_u32_e32 v209, 0x200, v208
	v_add_u32_e32 v6, 0, v4
	v_or_b32_e32 v0, 0xc00, v1
	v_and_b32_e32 v8, 28, v7
	s_mov_b64 s[6:7], 0
	s_movk_i32 s8, 0xc10
	v_mov_b32_e32 v9, 0
	v_mov_b64_e32 v[2:3], v[208:209]
	s_waitcnt lgkmcnt(0)
	s_barrier
	v_lshrrev_b32_e32 v0, 2, v208
	v_and_b32_e32 v1, 3, v208
	v_mul_u32_u24_e32 v2, 0x3040, v0
	v_lshl_add_u32 v2, v1, 4, v2
	v_add_u32_e32 v2, 0x3000, v2
	v_mov_b32_e32 v3, 0
	v_lshl_add_u64 v[2:3], s[16:17], 0, v[2:3]
	v_lshlrev_b32_e32 v4, 14, v1
	v_lshl_add_u32 v4, v0, 2, v4
	s_mov_b64 s[8:9], 0
	v_lshl_add_u64 v[6:7], v[2:3], 0, s[8:9]
	global_load_dwordx4 v[10:13], v[6:7], off
	s_add_u32 s8, s8, 0x182000
	s_addc_u32 s9, s9, 0
	v_lshl_add_u64 v[6:7], v[2:3], 0, s[8:9]
	global_load_dwordx4 v[14:17], v[6:7], off
	s_add_u32 s8, s8, 0x182000
	s_addc_u32 s9, s9, 0
	v_lshl_add_u64 v[6:7], v[2:3], 0, s[8:9]
	global_load_dwordx4 v[18:21], v[6:7], off
	s_add_u32 s8, s8, 0x182000
	s_addc_u32 s9, s9, 0
	v_lshl_add_u64 v[6:7], v[2:3], 0, s[8:9]
	global_load_dwordx4 v[22:25], v[6:7], off
	s_add_u32 s8, s8, 0x182000
	s_addc_u32 s9, s9, 0
	v_lshl_add_u64 v[6:7], v[2:3], 0, s[8:9]
	global_load_dwordx4 v[26:29], v[6:7], off
	s_add_u32 s8, s8, 0x182000
	s_addc_u32 s9, s9, 0
	v_lshl_add_u64 v[6:7], v[2:3], 0, s[8:9]
	global_load_dwordx4 v[30:33], v[6:7], off
	s_add_u32 s8, s8, 0x182000
	s_addc_u32 s9, s9, 0
	v_lshl_add_u64 v[6:7], v[2:3], 0, s[8:9]
	global_load_dwordx4 v[34:37], v[6:7], off
	s_add_u32 s8, s8, 0x182000
	s_addc_u32 s9, s9, 0
	v_lshl_add_u64 v[6:7], v[2:3], 0, s[8:9]
	global_load_dwordx4 v[38:41], v[6:7], off
	s_waitcnt vmcnt(7)
	ds_write_b32 v4, v10
	ds_write_b32 v4, v11 offset:4096
	ds_write_b32 v4, v12 offset:8192
	ds_write_b32 v4, v13 offset:12288
	s_waitcnt vmcnt(6)
	ds_write_b32 v4, v14 offset:512
	ds_write_b32 v4, v15 offset:4608
	ds_write_b32 v4, v16 offset:8704
	ds_write_b32 v4, v17 offset:12800
	s_waitcnt vmcnt(5)
	ds_write_b32 v4, v18 offset:1024
	ds_write_b32 v4, v19 offset:5120
	ds_write_b32 v4, v20 offset:9216
	ds_write_b32 v4, v21 offset:13312
	s_waitcnt vmcnt(4)
	ds_write_b32 v4, v22 offset:1536
	ds_write_b32 v4, v23 offset:5632
	ds_write_b32 v4, v24 offset:9728
	ds_write_b32 v4, v25 offset:13824
	s_waitcnt vmcnt(3)
	ds_write_b32 v4, v26 offset:2048
	ds_write_b32 v4, v27 offset:6144
	ds_write_b32 v4, v28 offset:10240
	ds_write_b32 v4, v29 offset:14336
	s_waitcnt vmcnt(2)
	ds_write_b32 v4, v30 offset:2560
	ds_write_b32 v4, v31 offset:6656
	ds_write_b32 v4, v32 offset:10752
	ds_write_b32 v4, v33 offset:14848
	s_waitcnt vmcnt(1)
	ds_write_b32 v4, v34 offset:3072
	ds_write_b32 v4, v35 offset:7168
	ds_write_b32 v4, v36 offset:11264
	ds_write_b32 v4, v37 offset:15360
	s_waitcnt vmcnt(0)
	ds_write_b32 v4, v38 offset:3584
	ds_write_b32 v4, v39 offset:7680
	ds_write_b32 v4, v40 offset:11776
	ds_write_b32 v4, v41 offset:15872
	s_cmpk_gt_i32 s36, 0x3fff
	s_waitcnt lgkmcnt(0)
	s_barrier
	s_cbranch_scc1 .LBB0_114
	v_mbcnt_lo_u32_b32 v0, -1, 0
	v_mbcnt_hi_u32_b32 v0, -1, v0
	v_and_b32_e32 v1, 64, v0
	v_add_u32_e32 v1, 64, v1
	v_xor_b32_e32 v2, 1, v0
	v_cmp_lt_i32_e32 vcc, v2, v1
	s_add_u32 s42, s40, 0x100000
	v_mov_b32_e32 v213, 0
	v_cndmask_b32_e32 v2, v0, v2, vcc
	v_lshlrev_b32_e32 v209, 2, v2
	v_xor_b32_e32 v2, 2, v0
	v_cmp_lt_i32_e32 vcc, v2, v1
	s_addc_u32 s43, s41, 0
	s_ashr_i32 s37, s36, 31
	v_cndmask_b32_e32 v2, v0, v2, vcc
	v_lshlrev_b32_e32 v211, 2, v2
	v_xor_b32_e32 v2, 4, v0
	v_cmp_lt_i32_e32 vcc, v2, v1
	v_lshlrev_b32_e32 v212, 4, v210
	v_lshl_add_u64 v[214:215], s[22:23], 0, v[212:213]
	v_cndmask_b32_e32 v2, v0, v2, vcc
	v_lshlrev_b32_e32 v238, 2, v2
	v_xor_b32_e32 v2, 8, v0
	v_cmp_lt_i32_e32 vcc, v2, v1
	s_mov_b32 s45, 0
	v_cmp_eq_u32_e64 s[6:7], 0, v210
	v_cndmask_b32_e32 v2, v0, v2, vcc
	v_lshlrev_b32_e32 v239, 2, v2
	v_xor_b32_e32 v2, 16, v0
	v_cmp_lt_i32_e32 vcc, v2, v1
	v_add_u32_e32 v242, 0, v212
	v_cmp_gt_u32_e64 s[8:9], 32, v210
	v_cndmask_b32_e32 v2, v0, v2, vcc
	v_lshlrev_b32_e32 v240, 2, v2
	v_xor_b32_e32 v2, 32, v0
	v_cmp_lt_i32_e32 vcc, v2, v1
	v_mov_b32_e32 v1, v213
	v_lshrrev_b32_e32 v243, 2, v210
	v_cndmask_b32_e32 v0, v0, v2, vcc
	v_lshlrev_b32_e32 v241, 2, v0
	v_and_b32_e32 v0, 16, v208
	v_cmp_eq_u32_e64 s[10:11], 0, v0
	v_and_b32_e32 v0, 8, v208
	v_cmp_eq_u32_e64 s[12:13], 0, v0
	v_and_b32_e32 v0, 4, v208
	v_cmp_eq_u32_e64 s[14:15], 0, v0
	v_and_b32_e32 v0, 3, v208
	v_cmp_eq_u32_e64 s[16:17], 0, v0
	v_and_b32_e32 v0, 60, v210
	v_lshl_add_u64 v[216:217], s[18:19], 0, v[0:1]
	s_lshl_b64 s[18:19], s[36:37], 2
	s_add_u32 s48, s18, 0x30000
	s_addc_u32 s49, s19, 0
	s_ashr_i32 s39, s38, 31
	s_lshl_b64 s[18:19], s[36:37], 11
	s_lshl_b64 s[22:23], s[38:39], 2
	v_lshl_or_b32 v218, v210, 3, s18
	v_mov_b32_e32 v219, s19
	s_lshl_b64 s[46:47], s[38:39], 11
	s_lshl_b64 s[18:19], s[36:37], 12
	s_add_u32 s18, s20, s18
	s_addc_u32 s19, s21, s19
	v_lshl_add_u64 v[0:1], s[18:19], 0, v[212:213]
	s_mov_b64 s[18:19], 0x800
	v_lshl_add_u64 v[220:221], v[0:1], 0, s[18:19]
	s_lshl_b64 s[20:21], s[38:39], 12
	v_mov_b32_e32 v212, 0x358637bd
	s_mov_b32 s37, 0xf800000
	v_mov_b32_e32 v244, 0x260
	s_mov_b32 s39, 0x4600000
	s_mov_b32 s50, 0xbfb8aa3b
	global_load_dwordx4 v[120:123], v[220:221], off offset:-2048 nt
	global_load_dwordx4 v[124:127], v[220:221], off offset:-1024 nt
	global_load_dwordx4 v[144:147], v[220:221], off nt
	global_load_dwordx4 v[148:151], v[220:221], off offset:1024 nt
	global_load_dword v245, v[216:217], off
	s_branch .LBB0_110

.LBB0_110:
	global_load_dwordx4 v[28:31], v[214:215], off
	global_load_dwordx4 v[32:35], v[214:215], off offset:1024
	global_load_dwordx4 v[36:39], v[214:215], off offset:2048
	global_load_dwordx4 v[40:43], v[214:215], off offset:3072
	s_waitcnt vmcnt(5) lgkmcnt(0)
	v_mov_b64_e32 v[12:13], v[120:121]
	v_mov_b64_e32 v[14:15], v[122:123]
	v_mov_b64_e32 v[8:9], v[124:125]
	v_mov_b64_e32 v[10:11], v[126:127]
	v_mov_b64_e32 v[4:5], v[144:145]
	v_mov_b64_e32 v[6:7], v[146:147]
	v_mov_b64_e32 v[0:1], v[148:149]
	v_mov_b64_e32 v[2:3], v[150:151]
	v_mul_f32_e32 v16, v13, v13
	v_mul_f32_e32 v17, v15, v15
	v_mul_f32_e32 v18, v9, v9
	v_mul_f32_e32 v19, v11, v11
	v_mul_f32_e32 v20, v5, v5
	v_mul_f32_e32 v21, v7, v7
	v_fmac_f32_e32 v16, v12, v12
	v_fmac_f32_e32 v17, v14, v14
	v_fmac_f32_e32 v18, v8, v8
	v_fmac_f32_e32 v19, v10, v10
	v_mul_f32_e32 v22, v1, v1
	v_mul_f32_e32 v23, v3, v3
	v_fmac_f32_e32 v20, v4, v4
	v_fmac_f32_e32 v21, v6, v6
	v_add_f32_e32 v16, v16, v17
	v_add_f32_e32 v17, v18, v19
	v_fmac_f32_e32 v22, v0, v0
	v_fmac_f32_e32 v23, v2, v2
	v_add_f32_e32 v18, v20, v21
	v_add_f32_e32 v16, v16, v17
	v_add_f32_e32 v16, v16, v18
	v_add_f32_e32 v17, v22, v23
	v_add_f32_e32 v16, v16, v17
	ds_bpermute_b32 v17, v209, v16
	s_waitcnt lgkmcnt(0)
	v_add_f32_e32 v16, v16, v17
	ds_bpermute_b32 v17, v211, v16
	s_waitcnt lgkmcnt(0)
	v_add_f32_e32 v16, v16, v17
	ds_bpermute_b32 v17, v238, v16
	s_waitcnt lgkmcnt(0)
	v_add_f32_e32 v16, v16, v17
	ds_bpermute_b32 v17, v239, v16
	s_waitcnt lgkmcnt(0)
	v_add_f32_e32 v16, v16, v17
	ds_bpermute_b32 v17, v240, v16
	s_waitcnt lgkmcnt(0)
	v_add_f32_e32 v16, v16, v17
	ds_bpermute_b32 v17, v241, v16
	s_waitcnt lgkmcnt(0)
	v_add_f32_e32 v16, v16, v17
	s_and_saveexec_b64 s[18:19], s[6:7]
	s_cbranch_execz .LBB0_112
	s_add_u32 s52, s40, s48
	s_addc_u32 s53, s41, s49
	global_store_dword v213, v16, s[52:53]
.LBB0_112:
	s_or_b64 exec, exec, s[18:19]
	v_fmamk_f32 v16, v16, 0x3a800000, v212
	v_mul_f32_e32 v17, 0x4f800000, v16
	v_cmp_gt_f32_e32 vcc, s37, v16
	s_nop 1
	v_cndmask_b32_e32 v22, v16, v17, vcc
	v_sqrt_f32_e32 v23, v22
	v_lshl_add_u64 v[16:17], s[40:41], 0, v[218:219]
	v_add_u32_e32 v24, -1, v23
	v_add_u32_e32 v25, 1, v23
	v_fma_f32 v26, -v24, v23, v22
	v_fma_f32 v27, -v25, v23, v22
	v_cmp_ge_f32_e64 s[18:19], 0, v26
	s_nop 1
	v_cndmask_b32_e64 v23, v23, v24, s[18:19]
	v_cmp_lt_f32_e64 s[18:19], 0, v27
	s_nop 1
	v_cndmask_b32_e64 v23, v23, v25, s[18:19]
	v_mul_f32_e32 v24, 0x37800000, v23
	v_cndmask_b32_e32 v23, v23, v24, vcc
	v_cmp_class_f32_e32 vcc, v22, v244
	s_nop 1
	v_cndmask_b32_e32 v22, v23, v22, vcc
	v_div_scale_f32 v23, s[18:19], v22, v22, 1.0
	v_rcp_f32_e32 v24, v23
	v_add_co_u32_e32 v16, vcc, s39, v16
	v_fma_f32 v26, -v23, v24, 1.0
	s_nop 0
	v_addc_co_u32_e32 v17, vcc, 0, v17, vcc
	v_div_scale_f32 v25, vcc, 1.0, v22, 1.0
	v_fmac_f32_e32 v24, v26, v24
	v_mul_f32_e32 v26, v25, v24
	v_fma_f32 v27, -v23, v26, v25
	v_fmac_f32_e32 v26, v27, v24
	v_fma_f32 v23, -v23, v26, v25
	v_div_fmas_f32 v23, v23, v24, v26
	v_div_fixup_f32 v22, v23, v22, 1.0
	v_pk_mul_f32 v[12:13], v[12:13], v[22:23] op_sel_hi:[1,0]
	v_pk_mul_f32 v[14:15], v[14:15], v[22:23] op_sel_hi:[1,0]
	v_pk_mul_f32 v[8:9], v[8:9], v[22:23] op_sel_hi:[1,0]
	v_pk_mul_f32 v[10:11], v[10:11], v[22:23] op_sel_hi:[1,0]
	v_pk_mul_f32 v[4:5], v[4:5], v[22:23] op_sel_hi:[1,0]
	v_pk_mul_f32 v[6:7], v[6:7], v[22:23] op_sel_hi:[1,0]
	v_pk_mul_f32 v[0:1], v[0:1], v[22:23] op_sel_hi:[1,0]
	v_pk_mul_f32 v[2:3], v[2:3], v[22:23] op_sel_hi:[1,0]
	s_waitcnt vmcnt(1)
	v_pk_mul_f32 v[222:223], v[14:15], v[30:31]
	v_pk_mul_f32 v[224:225], v[12:13], v[28:29]
	v_cvt_pk_bf16_f32 v13, v222, v223
	s_nop 0
	v_cvt_pk_bf16_f32 v12, v224, v225
	global_store_dwordx2 v[16:17], v[12:13], off
	v_pk_mul_f32 v[228:229], v[10:11], v[34:35]
	v_pk_mul_f32 v[232:233], v[8:9], v[32:33]
	v_cvt_pk_bf16_f32 v9, v228, v229
	s_nop 0
	v_cvt_pk_bf16_f32 v8, v232, v233
	global_store_dwordx2 v[16:17], v[8:9], off offset:512
	v_pk_mul_f32 v[226:227], v[6:7], v[38:39]
	v_pk_mul_f32 v[230:231], v[4:5], v[36:37]
	v_cvt_pk_bf16_f32 v5, v226, v227
	s_nop 0
	v_cvt_pk_bf16_f32 v4, v230, v231
	global_store_dwordx2 v[16:17], v[4:5], off offset:1024
	v_pk_mul_f32 v[234:235], v[2:3], v[42:43]
	v_pk_mul_f32 v[236:237], v[0:1], v[40:41]
	v_cvt_pk_bf16_f32 v1, v234, v235
	s_nop 0
	v_cvt_pk_bf16_f32 v0, v236, v237
	global_store_dwordx2 v[16:17], v[0:1], off offset:1536
	ds_read_b128 v[28:31], v242
	ds_read_b128 v[24:27], v242 offset:1024
	ds_read_b128 v[0:3], v242 offset:2048
	ds_read_b128 v[4:7], v242 offset:3072
	ds_read_b128 v[40:43], v242 offset:4096
	ds_read_b128 v[32:35], v242 offset:5120
	ds_read_b128 v[8:11], v242 offset:6144
	ds_read_b128 v[12:15], v242 offset:7168
	ds_read_b128 v[52:55], v242 offset:8192
	ds_read_b128 v[60:63], v242 offset:9216
	ds_read_b128 v[16:19], v242 offset:10240
	ds_read_b128 v[20:23], v242 offset:11264
	ds_read_b128 v[64:67], v242 offset:12288
	ds_read_b128 v[72:75], v242 offset:13312
	ds_read_b128 v[36:39], v242 offset:14336
	ds_read_b128 v[44:47], v242 offset:15360
	s_waitcnt lgkmcnt(14)
	v_fma_f32 v28, v224, v28, 0
	v_fmac_f32_e32 v28, v225, v29
	ds_read_b128 v[80:83], v242 offset:16384
	ds_read_b128 v[84:87], v242 offset:17408
	ds_read_b128 v[48:51], v242 offset:18432
	ds_read_b128 v[56:59], v242 offset:19456
	ds_read_b128 v[92:95], v242 offset:20480
	ds_read_b128 v[100:103], v242 offset:21504
	ds_read_b128 v[68:71], v242 offset:22528
	ds_read_b128 v[76:79], v242 offset:23552
	ds_read_b128 v[104:107], v242 offset:24576
	ds_read_b128 v[112:115], v242 offset:25600
	ds_read_b128 v[88:91], v242 offset:26624
	ds_read_b128 v[96:99], v242 offset:27648
	ds_read_b128 v[128:131], v242 offset:28672
	ds_read_b128 v[132:135], v242 offset:29696
	ds_read_b128 v[108:111], v242 offset:30720
	ds_read_b128 v[116:119], v242 offset:31744
	v_fmac_f32_e32 v28, v222, v30
	ds_read_b128 v[144:147], v242 offset:32768
	ds_read_b128 v[148:151], v242 offset:33792
	ds_read_b128 v[120:123], v242 offset:34816
	ds_read_b128 v[124:127], v242 offset:35840
	ds_read_b128 v[160:163], v242 offset:36864
	ds_read_b128 v[164:167], v242 offset:37888
	ds_read_b128 v[136:139], v242 offset:38912
	ds_read_b128 v[140:143], v242 offset:39936
	ds_read_b128 v[168:171], v242 offset:40960
	ds_read_b128 v[176:179], v242 offset:41984
	ds_read_b128 v[152:155], v242 offset:43008
	ds_read_b128 v[156:159], v242 offset:44032
	ds_read_b128 v[188:191], v242 offset:45056
	ds_read_b128 v[192:195], v242 offset:46080
	ds_read_b128 v[172:175], v242 offset:47104
	ds_read_b128 v[180:183], v242 offset:48128
	v_fmac_f32_e32 v28, v223, v31
	ds_read_b128 v[200:203], v242 offset:49152
	ds_read_b128 v[246:249], v242 offset:50176
	ds_read_b128 v[196:199], v242 offset:51200
	ds_read_b128 v[204:207], v242 offset:52224
	ds_read_b128 v[250:253], v242 offset:53248
	ds_read_b128 v[184:187], v242 offset:54272
	v_fma_f32 v24, v232, v24, 0
	s_waitcnt lgkmcnt(14)
	v_fmac_f32_e32 v28, v230, v0
	v_fmac_f32_e32 v24, v233, v25
	v_fmac_f32_e32 v28, v231, v1
	v_fma_f32 v64, v224, v64, 0
	v_fmac_f32_e32 v24, v228, v26
	v_fmac_f32_e32 v28, v226, v2
	v_fma_f32 v60, v232, v60, 0
	v_fmac_f32_e32 v64, v225, v65
	v_fmac_f32_e32 v24, v229, v27
	v_fmac_f32_e32 v28, v227, v3
	ds_read_b128 v[0:3], v242 offset:55296
	v_fmac_f32_e32 v60, v233, v61
	v_fmac_f32_e32 v64, v222, v66
	s_waitcnt lgkmcnt(2)
	v_fma_f32 v66, v224, v250, 0
	v_fmac_f32_e32 v24, v236, v4
	v_fmac_f32_e32 v60, v228, v62
	v_fmac_f32_e32 v66, v225, v251
	v_fmac_f32_e32 v24, v237, v5
	v_fmac_f32_e32 v60, v229, v63
	v_fmac_f32_e32 v66, v222, v252
	v_fmac_f32_e32 v24, v234, v6
	v_fmac_f32_e32 v60, v236, v20
	v_fmac_f32_e32 v24, v235, v7
	v_fmac_f32_e32 v66, v223, v253
	ds_read_b128 v[4:7], v242 offset:56320
	v_fmac_f32_e32 v60, v237, v21
	s_waitcnt lgkmcnt(2)
	v_fma_f32 v21, v232, v184, 0
	s_waitcnt lgkmcnt(1)
	v_fmac_f32_e32 v66, v230, v0
	v_fmac_f32_e32 v21, v233, v185
	v_fmac_f32_e32 v66, v231, v1
	v_fmac_f32_e32 v21, v228, v186
	v_fmac_f32_e32 v66, v226, v2
	v_fmac_f32_e32 v21, v229, v187
	v_fmac_f32_e32 v66, v227, v3
	ds_read_b128 v[0:3], v242 offset:57344
	s_waitcnt lgkmcnt(1)
	v_fmac_f32_e32 v21, v236, v4
	v_fmac_f32_e32 v21, v237, v5
	v_fmac_f32_e32 v21, v234, v6
	v_fmac_f32_e32 v21, v235, v7
	ds_read_b128 v[4:7], v242 offset:58368
	v_fmac_f32_e32 v60, v234, v22
	s_waitcnt lgkmcnt(1)
	v_fma_f32 v22, v224, v0, 0
	v_fmac_f32_e32 v22, v225, v1
	v_fmac_f32_e32 v22, v222, v2
	v_fmac_f32_e32 v22, v223, v3
	ds_read_b128 v[0:3], v242 offset:59392
	v_fmac_f32_e32 v60, v235, v23
	s_waitcnt lgkmcnt(1)
	v_fma_f32 v23, v232, v4, 0
	v_fmac_f32_e32 v23, v233, v5
	v_fmac_f32_e32 v23, v228, v6
	v_fmac_f32_e32 v23, v229, v7
	ds_read_b128 v[4:7], v242 offset:60416
	s_waitcnt lgkmcnt(1)
	v_fmac_f32_e32 v22, v230, v0
	v_fmac_f32_e32 v22, v231, v1
	v_fmac_f32_e32 v22, v226, v2
	v_fmac_f32_e32 v22, v227, v3
	ds_read_b128 v[0:3], v242 offset:61440
	s_waitcnt lgkmcnt(1)
	v_fmac_f32_e32 v23, v236, v4
	v_fmac_f32_e32 v23, v237, v5
	v_fma_f32 v40, v224, v40, 0
	v_fmac_f32_e32 v23, v234, v6
	v_fma_f32 v32, v232, v32, 0
	v_fmac_f32_e32 v40, v225, v41
	v_fmac_f32_e32 v23, v235, v7
	ds_read_b128 v[4:7], v242 offset:62464
	v_fmac_f32_e32 v32, v233, v33
	v_fmac_f32_e32 v40, v222, v42
	v_add_f32_e32 v22, v22, v23
	s_waitcnt lgkmcnt(1)
	v_fma_f32 v23, v224, v0, 0
	v_fma_f32 v52, v224, v52, 0
	v_fmac_f32_e32 v40, v223, v43
	v_fmac_f32_e32 v32, v228, v34
	v_fma_f32 v34, v224, v144, 0
	v_fma_f32 v43, v232, v148, 0
	v_fmac_f32_e32 v23, v225, v1
	v_fmac_f32_e32 v52, v225, v53
	v_fma_f32 v53, v224, v160, 0
	v_fmac_f32_e32 v32, v229, v35
	v_fma_f32 v35, v232, v164, 0
	v_fmac_f32_e32 v34, v225, v145
	v_fmac_f32_e32 v43, v233, v149
	v_fmac_f32_e32 v23, v222, v2
	v_fmac_f32_e32 v52, v222, v54
	v_fma_f32 v54, v224, v168, 0
	v_fma_f32 v61, v232, v176, 0
	v_fmac_f32_e32 v53, v225, v161
	v_fmac_f32_e32 v35, v233, v165
	v_fmac_f32_e32 v34, v222, v146
	v_fmac_f32_e32 v43, v228, v150
	v_fmac_f32_e32 v23, v223, v3
	ds_read_b128 v[0:3], v242 offset:63488
	v_fmac_f32_e32 v54, v225, v169
	v_fmac_f32_e32 v61, v233, v177
	v_fmac_f32_e32 v40, v230, v8
	v_fmac_f32_e32 v53, v222, v162
	v_fmac_f32_e32 v35, v228, v166
	v_fmac_f32_e32 v34, v223, v147
	v_fmac_f32_e32 v43, v229, v151
	v_add_f32_e32 v8, v28, v24
	s_waitcnt lgkmcnt(1)
	v_fma_f32 v24, v232, v4, 0
	v_fmac_f32_e32 v54, v222, v170
	v_fmac_f32_e32 v61, v228, v178
	v_fmac_f32_e32 v53, v223, v163
	v_fmac_f32_e32 v35, v229, v167
	v_fmac_f32_e32 v34, v230, v120
	v_fmac_f32_e32 v43, v236, v124
	v_fmac_f32_e32 v24, v233, v5
	v_fmac_f32_e32 v52, v223, v55
	v_fmac_f32_e32 v32, v236, v12
	v_fmac_f32_e32 v54, v223, v171
	v_fmac_f32_e32 v61, v229, v179
	v_fmac_f32_e32 v53, v230, v136
	v_fmac_f32_e32 v35, v236, v140
	v_fmac_f32_e32 v34, v231, v121
	v_fmac_f32_e32 v43, v237, v125
	v_fmac_f32_e32 v24, v228, v6
	v_fmac_f32_e32 v52, v230, v16
	v_fmac_f32_e32 v40, v231, v9
	v_fmac_f32_e32 v32, v237, v13
	v_fmac_f32_e32 v54, v230, v152
	v_fmac_f32_e32 v61, v236, v156
	v_fmac_f32_e32 v53, v231, v137
	v_fmac_f32_e32 v35, v237, v141
	v_fmac_f32_e32 v34, v226, v122
	v_fmac_f32_e32 v43, v234, v126
	v_fmac_f32_e32 v24, v229, v7
	ds_read_b128 v[4:7], v242 offset:64512
	v_fmac_f32_e32 v52, v231, v17
	v_fmac_f32_e32 v40, v226, v10
	v_fmac_f32_e32 v32, v234, v14
	v_fmac_f32_e32 v54, v231, v153
	v_fmac_f32_e32 v61, v237, v157
	v_fmac_f32_e32 v53, v226, v138
	v_fmac_f32_e32 v35, v234, v142
	v_fmac_f32_e32 v34, v227, v123
	v_fmac_f32_e32 v43, v235, v127
	s_add_i32 s98, s36, s38
	s_cmpk_lt_i32 s98, 0x4000
	s_cbranch_scc0 .Lp0rows_nopf
	v_lshl_add_u64 v[160:161], v[220:221], 0, s[20:21]
	global_load_dwordx4 v[120:123], v[160:161], off offset:-2048 nt
	global_load_dwordx4 v[124:127], v[160:161], off offset:-1024 nt
	global_load_dwordx4 v[144:147], v[160:161], off nt
	global_load_dwordx4 v[148:151], v[160:161], off offset:1024 nt
.Lp0rows_nopf:
	s_waitcnt lgkmcnt(1)
	v_fmac_f32_e32 v23, v230, v0
	v_fma_f32 v29, v232, v72, 0
	v_fma_f32 v62, v224, v188, 0
	v_fma_f32 v55, v232, v192, 0
	v_fmac_f32_e32 v52, v226, v18
	v_fmac_f32_e32 v40, v227, v11
	v_fmac_f32_e32 v32, v235, v15
	v_fmac_f32_e32 v54, v226, v154
	v_fmac_f32_e32 v61, v234, v158
	v_fmac_f32_e32 v53, v227, v139
	v_fmac_f32_e32 v35, v235, v143
	v_add_f32_e32 v16, v34, v43
	v_fmac_f32_e32 v23, v231, v1
	v_fmac_f32_e32 v29, v233, v73
	v_fma_f32 v25, v224, v80, 0
	v_fma_f32 v30, v232, v84, 0
	v_fmac_f32_e32 v62, v225, v189
	v_fmac_f32_e32 v55, v233, v193
	v_fma_f32 v63, v224, v200, 0
	v_fma_f32 v65, v232, v246, 0
	v_fmac_f32_e32 v52, v227, v19
	v_add_f32_e32 v9, v40, v32
	v_fmac_f32_e32 v54, v227, v155
	v_fmac_f32_e32 v61, v235, v159
	v_add_f32_e32 v17, v53, v35
	v_fmac_f32_e32 v23, v226, v2
	v_cndmask_b32_e64 v1, v8, v16, s[8:9]
	v_fma_f32 v31, v224, v92, 0
	v_fma_f32 v26, v232, v100, 0
	v_fmac_f32_e32 v29, v228, v74
	v_fmac_f32_e32 v25, v225, v81
	v_fmac_f32_e32 v30, v233, v85
	v_fmac_f32_e32 v62, v222, v190
	v_fmac_f32_e32 v55, v228, v194
	v_fmac_f32_e32 v63, v225, v201
	v_fmac_f32_e32 v65, v233, v247
	v_add_f32_e32 v10, v52, v60
	v_add_f32_e32 v18, v54, v61
	v_fmac_f32_e32 v23, v227, v3
	ds_bpermute_b32 v1, v241, v1
	v_cndmask_b32_e64 v3, v9, v17, s[8:9]
	v_fmac_f32_e32 v31, v225, v93
	v_fmac_f32_e32 v26, v233, v101
	v_fmac_f32_e32 v64, v223, v67
	v_fmac_f32_e32 v29, v229, v75
	v_fmac_f32_e32 v25, v222, v82
	v_fmac_f32_e32 v30, v228, v86
	v_fmac_f32_e32 v62, v223, v191
	v_fmac_f32_e32 v55, v229, v195
	v_fmac_f32_e32 v63, v222, v202
	v_fmac_f32_e32 v65, v228, v248
	s_waitcnt lgkmcnt(1)
	v_fmac_f32_e32 v24, v236, v4
	ds_bpermute_b32 v3, v241, v3
	v_cndmask_b32_e64 v4, v10, v18, s[8:9]
	v_fmac_f32_e32 v31, v222, v94
	v_fmac_f32_e32 v26, v228, v102
	v_fmac_f32_e32 v64, v230, v36
	v_fmac_f32_e32 v29, v236, v44
	v_fmac_f32_e32 v25, v223, v83
	v_fmac_f32_e32 v30, v229, v87
	v_fmac_f32_e32 v62, v230, v172
	v_fmac_f32_e32 v55, v236, v180
	v_fmac_f32_e32 v63, v223, v203
	v_fmac_f32_e32 v65, v229, v249
	ds_bpermute_b32 v4, v241, v4
	v_fmac_f32_e32 v31, v223, v95
	v_fmac_f32_e32 v26, v229, v103
	v_fmac_f32_e32 v64, v231, v37
	v_fmac_f32_e32 v29, v237, v45
	v_fmac_f32_e32 v25, v230, v48
	v_fmac_f32_e32 v30, v236, v56
	v_fmac_f32_e32 v62, v231, v173
	v_fmac_f32_e32 v55, v237, v181
	v_fmac_f32_e32 v63, v230, v196
	v_fmac_f32_e32 v65, v236, v204
	v_fmac_f32_e32 v31, v230, v68
	v_fmac_f32_e32 v26, v236, v76
	v_fmac_f32_e32 v64, v226, v38
	v_fmac_f32_e32 v29, v234, v46
	v_fmac_f32_e32 v25, v231, v49
	v_fmac_f32_e32 v30, v237, v57
	v_fmac_f32_e32 v62, v226, v174
	v_fmac_f32_e32 v55, v234, v182
	v_fmac_f32_e32 v63, v231, v197
	v_fmac_f32_e32 v65, v237, v205
	v_cndmask_b32_e64 v2, v16, v8, s[8:9]
	v_fmac_f32_e32 v31, v231, v69
	v_fmac_f32_e32 v26, v237, v77
	v_fmac_f32_e32 v64, v227, v39
	v_fmac_f32_e32 v29, v235, v47
	v_fmac_f32_e32 v25, v226, v50
	v_fmac_f32_e32 v30, v234, v58
	v_fmac_f32_e32 v62, v227, v175
	v_fmac_f32_e32 v55, v235, v183
	v_fmac_f32_e32 v63, v226, v198
	v_fmac_f32_e32 v65, v234, v206
	s_waitcnt lgkmcnt(2)
	v_add_f32_e32 v1, v2, v1
	v_cndmask_b32_e64 v2, v17, v9, s[8:9]
	v_fma_f32 v27, v224, v104, 0
	v_fma_f32 v33, v232, v112, 0
	v_fma_f32 v41, v224, v128, 0
	v_fma_f32 v42, v232, v132, 0
	v_fmac_f32_e32 v31, v226, v70
	v_fmac_f32_e32 v26, v234, v78
	v_add_f32_e32 v11, v64, v29
	v_fmac_f32_e32 v25, v227, v51
	v_fmac_f32_e32 v30, v235, v59
	v_add_f32_e32 v19, v62, v55
	v_fmac_f32_e32 v63, v227, v199
	v_fmac_f32_e32 v65, v235, v207
	s_waitcnt lgkmcnt(1)
	v_add_f32_e32 v2, v2, v3
	v_cndmask_b32_e64 v3, v18, v10, s[8:9]
	v_fmac_f32_e32 v27, v225, v105
	v_fmac_f32_e32 v33, v233, v113
	v_fmac_f32_e32 v41, v225, v129
	v_fmac_f32_e32 v42, v233, v133
	v_fmac_f32_e32 v31, v227, v71
	v_fmac_f32_e32 v26, v235, v79
	v_add_f32_e32 v12, v25, v30
	v_add_f32_e32 v20, v63, v65
	v_fmac_f32_e32 v24, v237, v5
	s_waitcnt lgkmcnt(0)
	v_add_f32_e32 v3, v3, v4
	v_cndmask_b32_e64 v4, v11, v19, s[8:9]
	v_fmac_f32_e32 v27, v222, v106
	v_fmac_f32_e32 v33, v228, v114
	v_fmac_f32_e32 v41, v222, v130
	v_fmac_f32_e32 v42, v228, v134
	v_add_f32_e32 v13, v31, v26
	v_add_f32_e32 v21, v66, v21
	v_fmac_f32_e32 v24, v234, v6
	ds_bpermute_b32 v4, v241, v4
	v_cndmask_b32_e64 v6, v12, v20, s[8:9]
	v_fmac_f32_e32 v27, v223, v107
	v_fmac_f32_e32 v33, v229, v115
	v_fmac_f32_e32 v41, v223, v131
	v_fmac_f32_e32 v42, v229, v135
	v_fmac_f32_e32 v24, v235, v7
	ds_bpermute_b32 v6, v241, v6
	v_cndmask_b32_e64 v7, v13, v21, s[8:9]
	v_fmac_f32_e32 v27, v230, v88
	v_fmac_f32_e32 v33, v236, v96
	v_fmac_f32_e32 v41, v230, v108
	v_fmac_f32_e32 v42, v236, v116
	ds_bpermute_b32 v7, v241, v7
	v_fmac_f32_e32 v27, v231, v89
	v_fmac_f32_e32 v33, v237, v97
	v_fmac_f32_e32 v41, v231, v109
	v_fmac_f32_e32 v42, v237, v117
	v_fmac_f32_e32 v27, v226, v90
	v_fmac_f32_e32 v33, v234, v98
	v_fmac_f32_e32 v41, v226, v110
	v_fmac_f32_e32 v42, v234, v118
	v_cndmask_b32_e64 v5, v19, v11, s[8:9]
	v_fmac_f32_e32 v27, v227, v91
	v_fmac_f32_e32 v33, v235, v99
	v_fmac_f32_e32 v41, v227, v111
	v_fmac_f32_e32 v42, v235, v119
	s_waitcnt lgkmcnt(2)
	v_add_f32_e32 v4, v5, v4
	v_cndmask_b32_e64 v5, v20, v12, s[8:9]
	v_add_f32_e32 v14, v27, v33
	v_add_f32_e32 v15, v41, v42
	v_add_f32_e32 v0, v23, v24
	s_waitcnt lgkmcnt(1)
	v_add_f32_e32 v5, v5, v6
	v_cndmask_b32_e64 v6, v21, v13, s[8:9]
	s_waitcnt lgkmcnt(0)
	v_add_f32_e32 v6, v6, v7
	v_cndmask_b32_e64 v7, v14, v22, s[8:9]
	v_cndmask_b32_e64 v9, v15, v0, s[8:9]
	ds_bpermute_b32 v7, v241, v7
	ds_bpermute_b32 v9, v241, v9
	v_cndmask_b32_e64 v8, v22, v14, s[8:9]
	v_cndmask_b32_e64 v0, v0, v15, s[8:9]
	v_cndmask_b32_e64 v10, v1, v5, s[10:11]
	s_waitcnt lgkmcnt(1)
	v_add_f32_e32 v7, v8, v7
	s_waitcnt lgkmcnt(0)
	v_add_f32_e32 v0, v0, v9
	v_cndmask_b32_e64 v1, v5, v1, s[10:11]
	v_cndmask_b32_e64 v5, v2, v6, s[10:11]
	v_cndmask_b32_e64 v2, v6, v2, s[10:11]
	v_cndmask_b32_e64 v6, v3, v7, s[10:11]
	v_cndmask_b32_e64 v8, v4, v0, s[10:11]
	ds_bpermute_b32 v10, v240, v10
	ds_bpermute_b32 v5, v240, v5
	ds_bpermute_b32 v6, v240, v6
	ds_bpermute_b32 v8, v240, v8
	v_cndmask_b32_e64 v3, v7, v3, s[10:11]
	v_cndmask_b32_e64 v0, v0, v4, s[10:11]
	s_waitcnt lgkmcnt(3)
	v_add_f32_e32 v1, v1, v10
	s_waitcnt lgkmcnt(2)
	v_add_f32_e32 v2, v2, v5
	s_waitcnt lgkmcnt(1)
	v_add_f32_e32 v3, v3, v6
	s_waitcnt lgkmcnt(0)
	v_add_f32_e32 v0, v0, v8
	v_cndmask_b32_e64 v4, v1, v3, s[12:13]
	v_cndmask_b32_e64 v5, v2, v0, s[12:13]
	ds_bpermute_b32 v4, v239, v4
	ds_bpermute_b32 v5, v239, v5
	v_cndmask_b32_e64 v1, v3, v1, s[12:13]
	v_cndmask_b32_e64 v0, v0, v2, s[12:13]
	s_waitcnt lgkmcnt(1)
	v_add_f32_e32 v1, v1, v4
	s_waitcnt lgkmcnt(0)
	v_add_f32_e32 v0, v0, v5
	v_cndmask_b32_e64 v2, v1, v0, s[14:15]
	ds_bpermute_b32 v2, v238, v2
	v_cndmask_b32_e64 v0, v0, v1, s[14:15]
	s_waitcnt lgkmcnt(0)
	v_add_f32_e32 v0, v0, v2
	ds_bpermute_b32 v1, v211, v0
	s_waitcnt lgkmcnt(0)
	v_add_f32_e32 v0, v0, v1
	ds_bpermute_b32 v1, v209, v0
	s_and_saveexec_b64 s[18:19], s[16:17]
	s_cbranch_execz .LBB0_109
	s_waitcnt lgkmcnt(0)
	v_add_f32_e32 v0, v0, v1
	s_ashr_i32 s44, s36, 8
	s_and_b32 s51, s36, 0xfff
	v_add_f32_e32 v2, v0, v245
	v_mul_f32_e64 v0, |v2|, s50
	v_exp_f32_e32 v3, v0
	v_and_or_b32 v0, s44, -16, v243
	v_ashrrev_i32_e32 v1, 31, v0
	v_lshlrev_b64 v[0:1], 14, v[0:1]
	v_add_f32_e32 v3, 1.0, v3
	v_log_f32_e32 v3, v3
	s_lshl_b32 s44, s51, 2
	v_lshl_add_u64 v[0:1], s[42:43], 0, v[0:1]
	v_min_f32_e32 v2, 0, v2
	v_fmac_f32_e32 v2, 0xbf317218, v3
	v_lshl_add_u64 v[0:1], v[0:1], 0, s[44:45]
	global_store_dword v[0:1], v2, off
	s_branch .LBB0_109

	.amdhsa_kernel _Z14fwd_megakernel4Args
		.amdhsa_group_segment_fixed_size 0
		.amdhsa_private_segment_fixed_size 0
		.amdhsa_kernarg_size 440
		.amdhsa_user_sgpr_count 2
		.amdhsa_user_sgpr_dispatch_ptr 0
		.amdhsa_user_sgpr_queue_ptr 0
		.amdhsa_user_sgpr_kernarg_segment_ptr 1
		.amdhsa_user_sgpr_dispatch_id 0
		.amdhsa_user_sgpr_kernarg_preload_length 0
		.amdhsa_user_sgpr_kernarg_preload_offset 0
		.amdhsa_user_sgpr_private_segment_size 0
		.amdhsa_uses_dynamic_stack 0
		.amdhsa_enable_private_segment 0
		.amdhsa_system_sgpr_workgroup_id_x 1
		.amdhsa_system_sgpr_workgroup_id_y 0
		.amdhsa_system_sgpr_workgroup_id_z 0
		.amdhsa_system_sgpr_workgroup_info 0
		.amdhsa_system_vgpr_workitem_id 2
		.amdhsa_next_free_vgpr 256
		.amdhsa_next_free_sgpr 102
		.amdhsa_accum_offset 256
		.amdhsa_reserve_vcc 1
		.amdhsa_float_round_mode_32 0
		.amdhsa_float_round_mode_16_64 0
		.amdhsa_float_denorm_mode_32 3
		.amdhsa_float_denorm_mode_16_64 3
		.amdhsa_dx10_clamp 1
		.amdhsa_ieee_mode 1
		.amdhsa_fp16_overflow 0
		.amdhsa_tg_split 0
		.amdhsa_exception_fp_ieee_invalid_op 0
		.amdhsa_exception_fp_denorm_src 0
		.amdhsa_exception_fp_ieee_div_zero 0
		.amdhsa_exception_fp_ieee_overflow 0
		.amdhsa_exception_fp_ieee_underflow 0
		.amdhsa_exception_fp_ieee_inexact 0
		.amdhsa_exception_int_div_zero 0
	.end_amdhsa_kernel

amdhsa.kernels:
  - .agpr_count:     0
    .args:
      - .offset:         0
        .size:           184
        .value_kind:     by_value
      - .offset:         184
        .size:           4
        .value_kind:     hidden_block_count_x
      - .offset:         188
        .size:           4
        .value_kind:     hidden_block_count_y
      - .offset:         192
        .size:           4
        .value_kind:     hidden_block_count_z
      - .offset:         196
        .size:           2
        .value_kind:     hidden_group_size_x
      - .offset:         198
        .size:           2
        .value_kind:     hidden_group_size_y
      - .offset:         200
        .size:           2
        .value_kind:     hidden_group_size_z
      - .offset:         202
        .size:           2
        .value_kind:     hidden_remainder_x
      - .offset:         204
        .size:           2
        .value_kind:     hidden_remainder_y
      - .offset:         206
        .size:           2
        .value_kind:     hidden_remainder_z
      - .offset:         224
        .size:           8
        .value_kind:     hidden_global_offset_x
      - .offset:         232
        .size:           8
        .value_kind:     hidden_global_offset_y
      - .offset:         240
        .size:           8
        .value_kind:     hidden_global_offset_z
      - .offset:         248
        .size:           2
        .value_kind:     hidden_grid_dims
      - .offset:         272
        .size:           8
        .value_kind:     hidden_multigrid_sync_arg
      - .offset:         304
        .size:           4
        .value_kind:     hidden_dynamic_lds_size
    .group_segment_fixed_size: 0
    .kernarg_segment_align: 8
    .kernarg_segment_size: 440
    .language:       OpenCL C
    .language_version:
      - 2
      - 0
    .max_flat_workgroup_size: 512
    .name:           _Z14fwd_megakernel4Args
    .private_segment_fixed_size: 0
    .sgpr_count:     108
    .sgpr_spill_count: 8
    .symbol:         _Z14fwd_megakernel4Args.kd
    .uniform_work_group_size: 1
    .uses_dynamic_stack: false
    .vgpr_count:     256
    .vgpr_spill_count: 0
    .wavefront_size: 64
